# weight conversion as a need-ordered queue: P0 keeps w_in[0] only, every grid seam (incl. seam 0) converts the next 2458-item chunk on waves 1-7
# speedup vs baseline: 1.0191x; 1.0090x over previous
; #define LAS __attribute__((address_space(3)))
; __global__ void __launch_bounds__(NWAVES * 64, 2) hybrid_fwd(Args args) {
;     extern __shared__ __attribute__((aligned(16))) unsigned char lds[];
;     cg::grid_group grid = cg::this_grid();
;     const int tid = threadIdx.x, lane = tid & 63, wave = __builtin_amdgcn_readfirstlane(tid >> 6);
;     const int G = gridDim.x, bx = blockIdx.x;
;     const int vcu = (G % 8 == 0) ? (bx % 8) * (G / 8) + bx / 8 : bx;
;     const int lo = args.ph_lo, hi = args.ph_hi;
;     if (tid < 16) ((volatile LAS unsigned*)((LAS unsigned char*)lds + LDS_BARST))[tid] = 0u;
;     __syncthreads();
;     const XcdBarrier xbar = xcd_barrier_post((unsigned*)args.in[17], (volatile LAS unsigned*)((LAS unsigned char*)lds + LDS_BARST));
_Z10hybrid_fwd4Args:
	s_mov_b32 s98, 8
	s_mov_b32 s99, 0xc00
	s_mov_b32 s100, 0
	s_mov_b32 s101, 0
	s_load_dwordx2 s[88:89], s[0:1], 0x98
	s_mov_b64 s[84:85], s[0:1]
	s_add_u32 s20, s84, 0x98
	s_mov_b32 s80, s2
	s_addc_u32 s21, s85, 0
	v_and_b32_e32 v169, 0x3ff, v0
	s_waitcnt lgkmcnt(0)
	s_and_b32 s0, s88, 7
	v_readfirstlane_b32 s3, v169
	s_cmp_lg_u32 s0, 0
	v_writelane_b32 v254, s80, 0
	s_cbranch_scc1 .LBB0_2
	s_ashr_i32 s1, s80, 31
	s_lshr_b32 s1, s1, 29
	s_add_i32 s1, s80, s1
	s_and_b32 s2, s1, -8
	s_ashr_i32 s0, s88, 3
	s_sub_i32 s2, s80, s2
	s_mul_i32 s0, s0, s2
	s_ashr_i32 s1, s1, 3
	s_add_i32 s0, s0, s1
	v_writelane_b32 v254, s0, 0

.LBB0_153:
	s_or_b64 exec, exec, s[0:1]
	v_readfirstlane_b32 s101, v169
	s_nop 3
	s_lshr_b32 s101, s101, 6
	s_cmp_eq_u32 s101, 0
	s_cbranch_scc1 .Lcv_skip_Z
	s_mov_b32 s100, 0
	s_cmp_gt_u32 s100, 18
	s_cbranch_scc1 .Lcv_skip_Z
	s_mul_i32 s100, s100, 2458
	s_add_i32 s100, s100, 3072
	s_add_i32 s99, s100, 2458
	s_min_i32 s99, s99, 0xc000
	s_sub_i32 s100, s100, 1
	s_mov_b32 s98, 7
	s_mov_b32 s101, 6
	v_readfirstlane_b32 s3, v169
	s_branch .Lcv_entry

.Lcv_ret_Z:
	s_barrier

; __device__ __forceinline__ unsigned xb_ld(unsigned* p)              { return __hip_atomic_load(p, __ATOMIC_RELAXED, __HIP_MEMORY_SCOPE_AGENT); }
; __device__ __forceinline__ unsigned xb_add(unsigned* p, unsigned v) { return __hip_atomic_fetch_add(p, v, __ATOMIC_RELAXED, __HIP_MEMORY_SCOPE_AGENT); }
; #define XB_SPIN(cond, bar) do { unsigned _sp = 0; while (cond) { __builtin_amdgcn_s_sleep(1); \
;     if ((++_sp & 255u) == 0u) { if (xb_ld(&(bar)[XB_TMO])) break; if (_sp > XB_SPIN_CAP) { atomicAdd(&(bar)[XB_TMO], 1u); break; } } } } while (0)
; __device__ __forceinline__ void xcd_barrier(const XcdBarrier& b) {
;     asm volatile("s_waitcnt vmcnt(0)" ::: "memory");
;     __syncthreads();
;     if (threadIdx.x == 0) {
;         unsigned* bar = b.bar;
;         __builtin_amdgcn_s_waitcnt(0);
;         unsigned nloc = b.st[0], nx = b.st[1];
;         if (nloc == 0u) { xcd_barrier_complete(bar, b.x, nloc, nx); b.st[0] = nloc; b.st[1] = nx; }
;         const unsigned old = xb_add(&bar[XB_XSUB(b.x)], 1u);
;         const unsigned gen = old / nloc;
;         if (old + 1u == (gen + 1u) * nloc) {
;             __builtin_amdgcn_fence(__ATOMIC_RELEASE, "agent");
;             asm volatile("s_waitcnt vmcnt(0)" ::: "memory");
;             const unsigned og = xb_add(&bar[XB_TOP], 1u);
;             const unsigned tg = og / nx;
;             if (og + 1u == (tg + 1u) * nx) xb_add(&bar[XB_TOPGEN], 1u);
;             else XB_SPIN(xb_ld(&bar[XB_TOPGEN]) == tg, bar);
;             __builtin_amdgcn_fence(__ATOMIC_ACQUIRE, "agent");
;             xb_add(&bar[XB_XGEN(b.x)], 1u);
;             asm volatile("s_waitcnt vmcnt(0)" ::: "memory");
;         } else {
;             XB_SPIN(xb_ld(&bar[XB_XGEN(b.x)]) == gen, bar);
;             __builtin_amdgcn_fence(__ATOMIC_ACQUIRE, "agent");
;             asm volatile("s_waitcnt vmcnt(0)" ::: "memory");
;         }
;     }
;     __syncthreads();
; }
.LBB0_156:
	s_or_b64 exec, exec, s[0:1]
	v_readfirstlane_b32 s101, v169
	s_nop 3
	s_lshr_b32 s101, s101, 6
	s_cmp_eq_u32 s101, 0
	s_cbranch_scc1 .Lcv_skip_E
	v_readlane_b32 s100, v255, 44
	s_nop 3
	s_mul_i32 s100, s100, 5
	s_add_i32 s100, s100, 5
	s_cmp_gt_u32 s100, 18
	s_cbranch_scc1 .Lcv_skip_E
	s_mul_i32 s100, s100, 2458
	s_add_i32 s100, s100, 3072
	s_add_i32 s99, s100, 2458
	s_min_i32 s99, s99, 0xc000
	s_sub_i32 s100, s100, 1
	s_mov_b32 s98, 7
	s_mov_b32 s101, 5
	v_readfirstlane_b32 s3, v169
	s_branch .Lcv_entry

; __device__ __forceinline__ unsigned xb_ld(unsigned* p)              { return __hip_atomic_load(p, __ATOMIC_RELAXED, __HIP_MEMORY_SCOPE_AGENT); }
; __device__ __forceinline__ unsigned xb_add(unsigned* p, unsigned v) { return __hip_atomic_fetch_add(p, v, __ATOMIC_RELAXED, __HIP_MEMORY_SCOPE_AGENT); }
; #define XB_SPIN(cond, bar) do { unsigned _sp = 0; while (cond) { __builtin_amdgcn_s_sleep(1); \
;     if ((++_sp & 255u) == 0u) { if (xb_ld(&(bar)[XB_TMO])) break; if (_sp > XB_SPIN_CAP) { atomicAdd(&(bar)[XB_TMO], 1u); break; } } } } while (0)
; __device__ __forceinline__ void xcd_barrier(const XcdBarrier& b) {
;     asm volatile("s_waitcnt vmcnt(0)" ::: "memory");
;     __syncthreads();
;     if (threadIdx.x == 0) {
;         unsigned* bar = b.bar;
;         __builtin_amdgcn_s_waitcnt(0);
;         unsigned nloc = b.st[0], nx = b.st[1];
;         if (nloc == 0u) { xcd_barrier_complete(bar, b.x, nloc, nx); b.st[0] = nloc; b.st[1] = nx; }
;         const unsigned old = xb_add(&bar[XB_XSUB(b.x)], 1u);
;         const unsigned gen = old / nloc;
;         if (old + 1u == (gen + 1u) * nloc) {
;             __builtin_amdgcn_fence(__ATOMIC_RELEASE, "agent");
;             asm volatile("s_waitcnt vmcnt(0)" ::: "memory");
;             const unsigned og = xb_add(&bar[XB_TOP], 1u);
;             const unsigned tg = og / nx;
;             if (og + 1u == (tg + 1u) * nx) xb_add(&bar[XB_TOPGEN], 1u);
;             else XB_SPIN(xb_ld(&bar[XB_TOPGEN]) == tg, bar);
;             __builtin_amdgcn_fence(__ATOMIC_ACQUIRE, "agent");
;             xb_add(&bar[XB_XGEN(b.x)], 1u);
;             asm volatile("s_waitcnt vmcnt(0)" ::: "memory");
;         } else {
;             XB_SPIN(xb_ld(&bar[XB_XGEN(b.x)]) == gen, bar);
;             __builtin_amdgcn_fence(__ATOMIC_ACQUIRE, "agent");
;             asm volatile("s_waitcnt vmcnt(0)" ::: "memory");
;         }
;     }
;     __syncthreads();
; }
.LBB0_292:
	s_or_b64 exec, exec, s[0:1]
	v_readfirstlane_b32 s101, v169
	s_nop 3
	s_lshr_b32 s101, s101, 6
	s_cmp_eq_u32 s101, 0
	s_cbranch_scc1 .Lcv_skip_A
	v_readlane_b32 s100, v255, 44
	s_nop 3
	s_mul_i32 s100, s100, 5
	s_add_i32 s100, s100, 1
	s_cmp_gt_u32 s100, 18
	s_cbranch_scc1 .Lcv_skip_A
	s_mul_i32 s100, s100, 2458
	s_add_i32 s100, s100, 3072
	s_add_i32 s99, s100, 2458
	s_min_i32 s99, s99, 0xc000
	s_sub_i32 s100, s100, 1
	s_mov_b32 s98, 7
	s_mov_b32 s101, 1
	v_readfirstlane_b32 s3, v169
	s_branch .Lcv_entry

; __device__ __forceinline__ unsigned xb_ld(unsigned* p)              { return __hip_atomic_load(p, __ATOMIC_RELAXED, __HIP_MEMORY_SCOPE_AGENT); }
; __device__ __forceinline__ unsigned xb_add(unsigned* p, unsigned v) { return __hip_atomic_fetch_add(p, v, __ATOMIC_RELAXED, __HIP_MEMORY_SCOPE_AGENT); }
; #define XB_SPIN(cond, bar) do { unsigned _sp = 0; while (cond) { __builtin_amdgcn_s_sleep(1); \
;     if ((++_sp & 255u) == 0u) { if (xb_ld(&(bar)[XB_TMO])) break; if (_sp > XB_SPIN_CAP) { atomicAdd(&(bar)[XB_TMO], 1u); break; } } } } while (0)
; __device__ __forceinline__ void xcd_barrier(const XcdBarrier& b) {
;     asm volatile("s_waitcnt vmcnt(0)" ::: "memory");
;     __syncthreads();
;     if (threadIdx.x == 0) {
;         unsigned* bar = b.bar;
;         __builtin_amdgcn_s_waitcnt(0);
;         unsigned nloc = b.st[0], nx = b.st[1];
;         if (nloc == 0u) { xcd_barrier_complete(bar, b.x, nloc, nx); b.st[0] = nloc; b.st[1] = nx; }
;         const unsigned old = xb_add(&bar[XB_XSUB(b.x)], 1u);
;         const unsigned gen = old / nloc;
;         if (old + 1u == (gen + 1u) * nloc) {
;             __builtin_amdgcn_fence(__ATOMIC_RELEASE, "agent");
;             asm volatile("s_waitcnt vmcnt(0)" ::: "memory");
;             const unsigned og = xb_add(&bar[XB_TOP], 1u);
;             const unsigned tg = og / nx;
;             if (og + 1u == (tg + 1u) * nx) xb_add(&bar[XB_TOPGEN], 1u);
;             else XB_SPIN(xb_ld(&bar[XB_TOPGEN]) == tg, bar);
;             __builtin_amdgcn_fence(__ATOMIC_ACQUIRE, "agent");
;             xb_add(&bar[XB_XGEN(b.x)], 1u);
;             asm volatile("s_waitcnt vmcnt(0)" ::: "memory");
;         } else {
;             XB_SPIN(xb_ld(&bar[XB_XGEN(b.x)]) == gen, bar);
;             __builtin_amdgcn_fence(__ATOMIC_ACQUIRE, "agent");
;             asm volatile("s_waitcnt vmcnt(0)" ::: "memory");
;         }
;     }
;     __syncthreads();
; }
.LBB0_435:
	s_or_b64 exec, exec, s[0:1]
	v_readfirstlane_b32 s101, v169
	s_nop 3
	s_lshr_b32 s101, s101, 6
	s_cmp_eq_u32 s101, 0
	s_cbranch_scc1 .Lcv_skip_B
	v_readlane_b32 s100, v255, 44
	s_nop 3
	s_mul_i32 s100, s100, 5
	s_add_i32 s100, s100, 2
	s_cmp_gt_u32 s100, 18
	s_cbranch_scc1 .Lcv_skip_B
	s_mul_i32 s100, s100, 2458
	s_add_i32 s100, s100, 3072
	s_add_i32 s99, s100, 2458
	s_min_i32 s99, s99, 0xc000
	s_sub_i32 s100, s100, 1
	s_mov_b32 s98, 7
	s_mov_b32 s101, 2
	v_readfirstlane_b32 s3, v169
	s_branch .Lcv_entry

; __device__ __forceinline__ unsigned xb_ld(unsigned* p)              { return __hip_atomic_load(p, __ATOMIC_RELAXED, __HIP_MEMORY_SCOPE_AGENT); }
; __device__ __forceinline__ unsigned xb_add(unsigned* p, unsigned v) { return __hip_atomic_fetch_add(p, v, __ATOMIC_RELAXED, __HIP_MEMORY_SCOPE_AGENT); }
; #define XB_SPIN(cond, bar) do { unsigned _sp = 0; while (cond) { __builtin_amdgcn_s_sleep(1); \
;     if ((++_sp & 255u) == 0u) { if (xb_ld(&(bar)[XB_TMO])) break; if (_sp > XB_SPIN_CAP) { atomicAdd(&(bar)[XB_TMO], 1u); break; } } } } while (0)
; __device__ __forceinline__ void xcd_barrier(const XcdBarrier& b) {
;     asm volatile("s_waitcnt vmcnt(0)" ::: "memory");
;     __syncthreads();
;     if (threadIdx.x == 0) {
;         unsigned* bar = b.bar;
;         __builtin_amdgcn_s_waitcnt(0);
;         unsigned nloc = b.st[0], nx = b.st[1];
;         if (nloc == 0u) { xcd_barrier_complete(bar, b.x, nloc, nx); b.st[0] = nloc; b.st[1] = nx; }
;         const unsigned old = xb_add(&bar[XB_XSUB(b.x)], 1u);
;         const unsigned gen = old / nloc;
;         if (old + 1u == (gen + 1u) * nloc) {
;             __builtin_amdgcn_fence(__ATOMIC_RELEASE, "agent");
;             asm volatile("s_waitcnt vmcnt(0)" ::: "memory");
;             const unsigned og = xb_add(&bar[XB_TOP], 1u);
;             const unsigned tg = og / nx;
;             if (og + 1u == (tg + 1u) * nx) xb_add(&bar[XB_TOPGEN], 1u);
;             else XB_SPIN(xb_ld(&bar[XB_TOPGEN]) == tg, bar);
;             __builtin_amdgcn_fence(__ATOMIC_ACQUIRE, "agent");
;             xb_add(&bar[XB_XGEN(b.x)], 1u);
;             asm volatile("s_waitcnt vmcnt(0)" ::: "memory");
;         } else {
;             XB_SPIN(xb_ld(&bar[XB_XGEN(b.x)]) == gen, bar);
;             __builtin_amdgcn_fence(__ATOMIC_ACQUIRE, "agent");
;             asm volatile("s_waitcnt vmcnt(0)" ::: "memory");
;         }
;     }
;     __syncthreads();
; }
.LBB0_536:
	s_or_b64 exec, exec, s[0:1]
	v_readfirstlane_b32 s101, v169
	s_nop 3
	s_lshr_b32 s101, s101, 6
	s_cmp_eq_u32 s101, 0
	s_cbranch_scc1 .Lcv_skip_C
	v_readlane_b32 s100, v255, 44
	s_nop 3
	s_mul_i32 s100, s100, 5
	s_add_i32 s100, s100, 3
	s_cmp_gt_u32 s100, 18
	s_cbranch_scc1 .Lcv_skip_C
	s_mul_i32 s100, s100, 2458
	s_add_i32 s100, s100, 3072
	s_add_i32 s99, s100, 2458
	s_min_i32 s99, s99, 0xc000
	s_sub_i32 s100, s100, 1
	s_mov_b32 s98, 7
	s_mov_b32 s101, 3
	v_readfirstlane_b32 s3, v169
	s_branch .Lcv_entry

; __device__ __forceinline__ unsigned xb_ld(unsigned* p)              { return __hip_atomic_load(p, __ATOMIC_RELAXED, __HIP_MEMORY_SCOPE_AGENT); }
; __device__ __forceinline__ unsigned xb_add(unsigned* p, unsigned v) { return __hip_atomic_fetch_add(p, v, __ATOMIC_RELAXED, __HIP_MEMORY_SCOPE_AGENT); }
; #define XB_SPIN(cond, bar) do { unsigned _sp = 0; while (cond) { __builtin_amdgcn_s_sleep(1); \
;     if ((++_sp & 255u) == 0u) { if (xb_ld(&(bar)[XB_TMO])) break; if (_sp > XB_SPIN_CAP) { atomicAdd(&(bar)[XB_TMO], 1u); break; } } } } while (0)
; __device__ __forceinline__ void xcd_barrier(const XcdBarrier& b) {
;     asm volatile("s_waitcnt vmcnt(0)" ::: "memory");
;     __syncthreads();
;     if (threadIdx.x == 0) {
;         unsigned* bar = b.bar;
;         __builtin_amdgcn_s_waitcnt(0);
;         unsigned nloc = b.st[0], nx = b.st[1];
;         if (nloc == 0u) { xcd_barrier_complete(bar, b.x, nloc, nx); b.st[0] = nloc; b.st[1] = nx; }
;         const unsigned old = xb_add(&bar[XB_XSUB(b.x)], 1u);
;         const unsigned gen = old / nloc;
;         if (old + 1u == (gen + 1u) * nloc) {
;             __builtin_amdgcn_fence(__ATOMIC_RELEASE, "agent");
;             asm volatile("s_waitcnt vmcnt(0)" ::: "memory");
;             const unsigned og = xb_add(&bar[XB_TOP], 1u);
;             const unsigned tg = og / nx;
;             if (og + 1u == (tg + 1u) * nx) xb_add(&bar[XB_TOPGEN], 1u);
;             else XB_SPIN(xb_ld(&bar[XB_TOPGEN]) == tg, bar);
;             __builtin_amdgcn_fence(__ATOMIC_ACQUIRE, "agent");
;             xb_add(&bar[XB_XGEN(b.x)], 1u);
;             asm volatile("s_waitcnt vmcnt(0)" ::: "memory");
;         } else {
;             XB_SPIN(xb_ld(&bar[XB_XGEN(b.x)]) == gen, bar);
;             __builtin_amdgcn_fence(__ATOMIC_ACQUIRE, "agent");
;             asm volatile("s_waitcnt vmcnt(0)" ::: "memory");
;         }
;     }
;     __syncthreads();
; }
.LBB0_615:
	s_or_b64 exec, exec, s[0:1]
	v_readfirstlane_b32 s101, v169
	s_nop 3
	s_lshr_b32 s101, s101, 6
	s_cmp_eq_u32 s101, 0
	s_cbranch_scc1 .Lcv_skip_D
	v_readlane_b32 s100, v255, 44
	s_nop 3
	s_mul_i32 s100, s100, 5
	s_add_i32 s100, s100, 4
	s_cmp_gt_u32 s100, 18
	s_cbranch_scc1 .Lcv_skip_D
	s_mul_i32 s100, s100, 2458
	s_add_i32 s100, s100, 3072
	s_add_i32 s99, s100, 2458
	s_min_i32 s99, s99, 0xc000
	s_sub_i32 s100, s100, 1
	s_mov_b32 s98, 7
	s_mov_b32 s101, 4
	v_readfirstlane_b32 s3, v169
	s_branch .Lcv_entry

; #define LAS __attribute__((address_space(3)))
; __device__ __forceinline__ unsigned xb_add(unsigned* p, unsigned v) { return __hip_atomic_fetch_add(p, v, __ATOMIC_RELAXED, __HIP_MEMORY_SCOPE_AGENT); }
; __device__ __forceinline__ unsigned xb_xcc_id() { return (unsigned)__builtin_amdgcn_s_getreg((3 << 11) | 20) & 0xFu; }
; __device__ __forceinline__ XcdBarrier xcd_barrier_post(unsigned* bar, volatile LAS unsigned* st) {
;     XcdBarrier b; b.bar = bar; b.x = xb_xcc_id(); b.st = st;
;     if (threadIdx.x == 0) (void)xb_add(&bar[XB_XCNT(b.x)], 1u);
;     return b;
; }
; __global__ void __launch_bounds__(NWAVES * 64, 2) hybrid_fwd(Args args) {
;     ...
;     for (int l = 0; l < DEPTH; ++l) {
;         const int p0 = 1 + 5 * l;
;         for (int rep = 0; rep < ((DUP & 2) ? 2 : 1); ++rep)
;         if (IN(p0) && !NO_PROJ) {
;             int ll = l, z = 0; asm volatile("" : "+s"(ll), "+s"(z));
;             unsigned char* w = (unsigned char*)args.in[z + 17]; float* xout = (float*)args.in[z + 16];
;             pg8::Gemm g{(const bf16*)(w + WS_XB), (const bf16*)(w + WS_WIN) + (size_t)ll * PW * D, T, PW, D, 1  }; pg8::StaticOrder S; S.init(T, PW, G, bx);
;             pg8::EpiProj E{(bf16*)(w + WS_PROJ), (const float*)(w + WS_SSQ) + (size_t)(2 * ll) * T * 32, args.in[z + 4] + ll * 64, args.in[z + 5] + ll * 64, PW};
;             pg8::gemm_phase<pg8::EpiProj, pg8::StaticOrder, true, true>((LAS unsigned char*)lds, g, S, E);
.Lcv_restore:
	s_getreg_b32 s0, hwreg(HW_REG_XCC_ID, 0, 4)
	s_and_b32 s2, s0, 15
	s_cmpk_lt_i32 s80, 0x300
	s_cselect_b64 s[4:5], -1, 0
	v_writelane_b32 v254, s4, 7
	s_ashr_i32 s1, s80, 31
	s_load_dwordx2 s[6:7], s[84:85], 0x88
	v_writelane_b32 v254, s5, 8
	v_writelane_b32 v254, s1, 9
	s_lshr_b32 s1, s1, 29
	s_add_i32 s1, s80, s1
	s_ashr_i32 s3, s1, 3
	s_and_b32 s1, s1, -8
	s_sub_i32 s1, s80, s1
	s_ashr_i32 s4, s88, 31
	v_writelane_b32 v254, s4, 10
	s_waitcnt lgkmcnt(0)
	s_add_u32 s4, s6, 0x200
	s_addc_u32 s5, s7, 0
	v_writelane_b32 v254, s4, 11
	s_mul_i32 s0, s89, s88
	v_mbcnt_lo_u32_b32 v0, -1, 0
	v_writelane_b32 v254, s5, 12
	s_add_u32 s4, s6, 0x1000
	s_addc_u32 s5, s7, 0
	v_writelane_b32 v254, s4, 13
	v_mbcnt_hi_u32_b32 v190, -1, v0
	v_and_b32_e32 v0, 64, v190
	v_writelane_b32 v254, s5, 14
	s_add_u32 s4, s6, 0x1100
	s_addc_u32 s5, s7, 0
	v_writelane_b32 v254, s4, 15
	s_movk_i32 s33, 0x300
	v_or_b32_e32 v189, 0x200, v177
	v_writelane_b32 v254, s5, 16
	s_add_u32 s4, s6, 0x1200
	s_addc_u32 s5, s7, 0
	v_writelane_b32 v254, s4, 17
	v_or_b32_e32 v183, 0x240, v177
	s_movk_i32 s64, 0x60
	v_writelane_b32 v254, s5, 18
	s_add_u32 s4, s6, 0x1300
	s_addc_u32 s5, s7, 0
	v_writelane_b32 v254, s4, 19
	s_cmp_eq_u32 s2, 15
	v_mov_b32_e32 v145, 0
	v_writelane_b32 v254, s5, 20
	s_cselect_b64 s[4:5], -1, 0
	v_writelane_b32 v254, s4, 21
	s_cmp_eq_u32 s2, 14
	v_mov_b32_e32 v186, 0x358637bd
	v_writelane_b32 v254, s5, 22
	s_cselect_b64 s[4:5], -1, 0
	v_writelane_b32 v254, s4, 23
	s_cmp_eq_u32 s2, 13
	v_mov_b32_e32 v187, 0x260
	v_writelane_b32 v254, s5, 24
	s_cselect_b64 s[4:5], -1, 0
	v_writelane_b32 v254, s4, 25
	s_cmp_eq_u32 s2, 12
	v_mov_b32_e32 v188, 1
	v_writelane_b32 v254, s5, 26
	s_cselect_b64 s[4:5], -1, 0
	v_writelane_b32 v254, s4, 27
	s_cmp_eq_u32 s2, 11
	v_xor_b32_e32 v191, 16, v190
	v_writelane_b32 v254, s5, 28
	s_cselect_b64 s[4:5], -1, 0
	v_writelane_b32 v254, s4, 29
	s_cmp_eq_u32 s2, 10
	v_add_u32_e32 v192, 64, v0
	v_writelane_b32 v254, s5, 30
	s_cselect_b64 s[4:5], -1, 0
	v_writelane_b32 v254, s4, 31
	s_cmp_eq_u32 s2, 9
	v_xor_b32_e32 v193, 32, v190
	v_writelane_b32 v254, s5, 32
	s_cselect_b64 s[4:5], -1, 0
	v_writelane_b32 v254, s4, 33
	s_cmp_eq_u32 s2, 8
	v_mov_b32_e32 v194, 31
	v_writelane_b32 v254, s5, 34
	s_cselect_b64 s[4:5], -1, 0
	v_writelane_b32 v254, s4, 35
	s_cmp_eq_u32 s2, 7
	v_mov_b64_e32 v[146:147], 0x300
	v_writelane_b32 v254, s5, 36
	s_cselect_b64 s[4:5], -1, 0
	v_writelane_b32 v254, s4, 37
	s_cmp_eq_u32 s2, 6
	v_mov_b64_e32 v[148:149], 0x2ff
	v_writelane_b32 v254, s5, 38
	s_cselect_b64 s[4:5], -1, 0
	v_writelane_b32 v254, s4, 39
	s_cmp_eq_u32 s2, 5
	v_mov_b32_e32 v195, 0x7f800000
	v_writelane_b32 v254, s5, 40
	s_cselect_b64 s[4:5], -1, 0
	v_writelane_b32 v254, s4, 41
	s_cmp_eq_u32 s2, 4
	v_mov_b32_e32 v196, 0x3000
	v_writelane_b32 v254, s5, 42
	s_cselect_b64 s[4:5], -1, 0
	v_writelane_b32 v254, s4, 43
	s_cmp_eq_u32 s2, 3
	v_mov_b64_e32 v[150:151], 0x1a380800
	v_writelane_b32 v254, s5, 44
	s_cselect_b64 s[4:5], -1, 0
	v_writelane_b32 v254, s4, 45
	s_cmp_eq_u32 s2, 2
	v_mov_b64_e32 v[152:153], 0xff
	v_writelane_b32 v254, s5, 46
	s_cselect_b64 s[4:5], -1, 0
	v_writelane_b32 v254, s4, 47
	s_cmp_eq_u32 s2, 1
	v_mov_b64_e32 v[154:155], 0x100
	v_writelane_b32 v254, s5, 48
	s_cselect_b64 s[4:5], -1, 0
	v_writelane_b32 v254, s4, 49
	s_cmp_eq_u32 s2, 0
	v_mov_b64_e32 v[156:157], 0x400
	v_writelane_b32 v254, s5, 50
	s_cselect_b64 s[4:5], -1, 0
	s_lshl_b32 s2, s2, 8
	v_writelane_b32 v254, s4, 51
	s_add_u32 s2, s6, s2
	v_mov_b64_e32 v[158:159], 0x3ff
	v_writelane_b32 v254, s5, 52
	s_addc_u32 s4, s7, 0
	s_add_u32 s8, s2, 0x1400
	s_addc_u32 s9, s4, 0
	v_writelane_b32 v254, s8, 53
	s_mov_b32 s65, 0xf800000
	s_movk_i32 s58, 0x2000
	v_writelane_b32 v254, s9, 54
	s_add_u32 s8, s2, 0x2400
	s_addc_u32 s9, s4, 0
	v_writelane_b32 v254, s8, 55
	s_add_u32 s4, s6, 0x3400
	s_addc_u32 s5, s7, 0
	v_writelane_b32 v254, s9, 56
	v_writelane_b32 v254, s4, 57
	s_movk_i32 s70, 0x3000
	s_movk_i32 s72, 0xff
	v_writelane_b32 v254, s5, 58
	s_add_u32 s4, s6, 0x3500
	s_addc_u32 s5, s7, 0
	v_writelane_b32 v254, s4, 59
	s_movk_i32 s6, 0x61
	s_movk_i32 s35, 0x1800
	v_writelane_b32 v254, s5, 60
	s_mov_b32 s26, 0
	v_readlane_b32 s2, v254, 0
	s_cmpk_lt_i32 s2, 0x100
	s_cselect_b64 s[4:5], -1, 0
	v_writelane_b32 v254, s4, 61
	s_cmpk_lt_i32 s80, 0x100
	s_mov_b64 s[36:37], 0x800
	v_writelane_b32 v254, s5, 62
	s_cselect_b64 s[4:5], -1, 0
	s_lshl_b32 s2, s1, 5
	v_writelane_b32 v254, s4, 63
	s_cmpk_lt_i32 s80, 0x400
	s_mov_b64 s[94:95], 0x80
	v_writelane_b32 v255, s5, 0
	s_cselect_b64 s[4:5], -1, 0
	v_writelane_b32 v255, s4, 1
	s_mov_b64 s[74:75], 0x1a381080
	s_mov_b64 s[82:83], 0x1800
	v_writelane_b32 v255, s5, 2
	s_load_dword s5, s[84:85], 0xa0
	s_lshl_b32 s4, s1, 7
	s_cmp_lt_i32 s1, 0
	s_cselect_b32 s6, s6, 0x60
	s_mov_b64 s[86:87], 0x2800
	s_waitcnt lgkmcnt(0)
; #define LAS __attribute__((address_space(3)))
; #define SEAM(k) do { } while (0)
; #define SEAM(k) do { if ((k) + 1 < hi) { if ((k) == 0) grid.sync(); else xcd_barrier(xbar); if (DUP & 16) { xcd_barrier(xbar); xcd_barrier(xbar); } } } while (0)
; __global__ void __launch_bounds__(NWAVES * 64, 2) hybrid_fwd(Args args) {
;     ...
;     for (int l = 0; l < DEPTH; ++l) {
;         const int p0 = 1 + 5 * l;
;         for (int rep = 0; rep < ((DUP & 2) ? 2 : 1); ++rep)
;         if (IN(p0) && !NO_PROJ) {
;             int ll = l, z = 0; asm volatile("" : "+s"(ll), "+s"(z));
;             unsigned char* w = (unsigned char*)args.in[z + 17]; float* xout = (float*)args.in[z + 16];
;             pg8::Gemm g{(const bf16*)(w + WS_XB), (const bf16*)(w + WS_WIN) + (size_t)ll * PW * D, T, PW, D, 1  }; pg8::StaticOrder S; S.init(T, PW, G, bx);
;             pg8::EpiProj E{(bf16*)(w + WS_PROJ), (const float*)(w + WS_SSQ) + (size_t)(2 * ll) * T * 32, args.in[z + 4] + ll * 64, args.in[z + 5] + ll * 64, PW};
;             pg8::gemm_phase<pg8::EpiProj, pg8::StaticOrder, true, true>((LAS unsigned char*)lds, g, S, E);
;             SEAM(p0);
;         }
;         for (int rep = 0; rep < ((DUP & 4) ? 2 : 1); ++rep)
;         if (IN(p0 + 1) && !NO_ATT) {
;             int ll = l, z = 0; asm volatile("" : "+s"(ll), "+s"(z));
;             unsigned char* w = (unsigned char*)args.in[z + 17]; float* xout = (float*)args.in[z + 16];
;             const bf16* PROJ = (const bf16*)(w + WS_PROJ); bf16* MIX = (bf16*)(w + WS_MIX); const float* BT = (const float*)(w + WS_BT);
;             const float lam_init = 0.8f - 0.6f * expf(-0.3f * (float)ll);
;             float a = args.in[z + 6][ll * 64 + lane] * args.in[z + 7][ll * 64 + lane], b2 = args.in[z + 8][ll * 64 + lane] * args.in[z + 9][ll * 64 + lane];
;             a = wave_sum(a); b2 = wave_sum(b2);
;             const float lam = expf(a) - expf(b2) + lam_init;
;             float gqm = fabsf(args.in[z + 4][ll * 64 + lane]), gkm = fabsf(args.in[z + 5][ll * 64 + lane]);
; #pragma unroll
;             for (int o = 1; o < 64; o <<= 1) { gqm = fmaxf(gqm, __shfl_xor(gqm, o)); gkm = fmaxf(gkm, __shfl_xor(gkm, o)); }
;             const float gqk = gqm * gkm;
	s_mul_i32 s0, s0, s5
	v_writelane_b32 v255, s0, 3
	s_mul_i32 s0, s1, 33
	s_mul_i32 s5, s1, 0x81
	s_mul_i32 s1, s1, s6
	s_cselect_b32 s2, s0, s2
	s_cselect_b32 s4, s5, s4
	s_add_i32 s1, s1, s3
	s_mul_hi_i32 s0, s1, 0x2aaaaaab
	s_lshr_b32 s5, s0, 31
	s_ashr_i32 s0, s0, 4
	s_add_i32 s0, s0, s5
	s_mul_i32 s5, s0, 0x60
	s_sub_i32 s1, s1, s5
	s_lshl_b32 s6, s0, 2
	s_bfe_i32 s0, s1, 0x80000
	s_bfe_u32 s0, s0, 0x2000d
	s_add_i32 s5, s1, s0
	s_bfe_i32 s0, s5, 0x80000
	s_and_b32 s5, s5, 0xfc
	s_sub_i32 s1, s1, s5
	s_sext_i32_i16 s7, s0
	s_sext_i32_i8 s1, s1
	s_add_i32 s8, s6, s1
	s_ashr_i32 s1, s7, 2
	v_writelane_b32 v255, s1, 4
	s_add_i32 s1, s2, s3
	s_ashr_i32 s2, s1, 31
	s_lshr_b32 s2, s2, 27
	s_add_i32 s2, s1, s2
	s_ashr_i32 s5, s2, 5
	s_and_b32 s2, s2, 0xffe0
	s_sub_i32 s1, s1, s2
	s_bfe_i32 s2, s1, 0x80000
	s_bfe_u32 s2, s2, 0x2000d
	s_add_i32 s6, s1, s2
	s_bfe_i32 s2, s6, 0x80000
	s_and_b32 s6, s6, 0xfc
	s_sub_i32 s1, s1, s6
	s_lshl_b32 s5, s5, 2
	s_sext_i32_i8 s1, s1
	s_add_i32 s10, s5, s1
	s_add_i32 s1, s4, s3
	s_ashr_i32 s3, s1, 31
	s_lshr_b32 s3, s3, 25
	s_add_i32 s3, s1, s3
	s_ashr_i32 s4, s3, 7
	s_and_b32 s3, s3, 0xff80
	s_sub_i32 s1, s1, s3
	s_bfe_i32 s3, s1, 0x80000
	s_bfe_u32 s3, s3, 0x2000d
	s_add_i32 s3, s1, s3
	s_lshl_b32 s5, s4, 2
	s_bfe_i32 s4, s3, 0x80000
	s_and_b32 s3, s3, 0xfc
	s_sub_i32 s1, s1, s3
	s_lshr_b32 s0, s7, 2
	s_sext_i32_i16 s7, s2
	s_sext_i32_i16 s6, s4
	s_sext_i32_i8 s1, s1
	s_lshr_b32 s2, s7, 2
	s_ashr_i32 s7, s7, 2
	s_lshr_b32 s4, s6, 2
	s_add_i32 s12, s5, s1
	s_ashr_i32 s1, s6, 2
	s_cmp_lg_u32 s12, -1
	v_writelane_b32 v255, s1, 5
	s_cselect_b64 s[14:15], -1, 0
	v_writelane_b32 v255, s14, 6
	s_lshl_b32 s1, s12, 8
	s_mov_b32 s6, s12
	v_writelane_b32 v255, s15, 7
	v_writelane_b32 v255, s1, 8
	s_ashr_i32 s13, s12, 31
	v_writelane_b32 v255, s6, 9
	s_lshl_b64 s[12:13], s[12:13], 20
	s_bfe_i64 s[4:5], s[4:5], 0x100000
	v_writelane_b32 v255, s7, 10
	v_writelane_b32 v255, s12, 11
	s_lshl_b64 s[4:5], s[4:5], 20
	s_cmp_lg_u32 s8, -1
	v_writelane_b32 v255, s13, 12
	v_writelane_b32 v255, s4, 13
	s_mov_b64 s[12:13], 0x1000
	s_mov_b32 s15, 0
	v_writelane_b32 v255, s5, 14
	s_cselect_b64 s[4:5], -1, 0
	v_writelane_b32 v255, s4, 15
	s_lshl_b32 s1, s8, 8
	s_ashr_i32 s9, s8, 31
	v_writelane_b32 v255, s5, 16
	v_writelane_b32 v255, s1, 17
	s_bfe_i64 s[0:1], s[0:1], 0x100000
	s_lshl_b64 s[0:1], s[0:1], 20
	v_writelane_b32 v255, s0, 18
	s_ashr_i32 s11, s10, 31
	s_add_i32 s57, 0, 0x19000
	v_writelane_b32 v255, s1, 19
	s_lshl_b32 s0, s10, 8
	v_writelane_b32 v255, s0, 20
	v_writelane_b32 v255, s7, 21
	s_lshl_b32 s0, s7, 8
	v_writelane_b32 v255, s0, 22
	s_bfe_i64 s[0:1], s[2:3], 0x100000
	s_lshl_b64 s[2:3], s[0:1], 20
	v_writelane_b32 v255, s2, 23
	s_lshl_b64 s[0:1], s[0:1], 22
	s_mov_b64 s[4:5], 0x1a381000
	v_writelane_b32 v255, s3, 24
	v_writelane_b32 v255, s0, 25
	s_add_i32 s2, 0, 0x18800
	s_nop 0
	v_writelane_b32 v255, s1, 26
	s_add_i32 s0, 0, 0x23fc0
	v_writelane_b32 v255, s0, 27
	s_add_i32 s0, 0, 0x23fc4
	v_writelane_b32 v255, s0, 28
	s_mov_b32 s0, s8
	v_writelane_b32 v255, s0, 29
	s_nop 1
	v_writelane_b32 v255, s1, 30
	s_lshl_b64 s[0:1], s[8:9], 20
	v_writelane_b32 v255, s0, 31
	s_nop 1
	v_writelane_b32 v255, s1, 32
	s_lshl_b64 s[0:1], s[10:11], 20
	v_writelane_b32 v255, s0, 33
	s_nop 1
	v_writelane_b32 v255, s1, 34
	s_mov_b32 s0, s10
	v_writelane_b32 v255, s0, 35
	s_nop 1
	v_writelane_b32 v255, s1, 36
	s_lshl_b64 s[0:1], s[10:11], 22
	v_writelane_b32 v255, s0, 37
	s_nop 1
	v_writelane_b32 v255, s1, 38
	v_writelane_b32 v255, s80, 39
	v_writelane_b32 v255, s84, 40
	s_nop 1
	v_writelane_b32 v255, s85, 41
	v_writelane_b32 v255, s88, 42
	s_nop 1
	v_writelane_b32 v255, s89, 43
	v_readlane_b32 s26, v255, 44
	v_readlane_b32 s27, v255, 45
	s_nop 3
	s_cmp_eq_u32 s101, 1
	s_cbranch_scc1 .Lcv_fix_A
	s_cmp_eq_u32 s101, 2
	s_cbranch_scc1 .Lcv_fix_B
	s_cmp_eq_u32 s101, 3
	s_cbranch_scc1 .Lcv_fix_C
	s_cmp_eq_u32 s101, 4
	s_cbranch_scc1 .Lcv_fix_D
	s_cmp_eq_u32 s101, 5
	s_cbranch_scc1 .Lcv_fix_E
	s_cmp_eq_u32 s101, 6
	s_cbranch_scc1 .Lcv_fix_Z
	s_endpgm

.Lcv_fix_E:
	s_mov_b32 s101, 0
	s_nop 3
	s_branch .Lcv_ret_E
.Lcv_fix_Z:
	s_mov_b32 s101, 0
	s_nop 3
	s_branch .Lcv_ret_Z
